# strategy 4a on the GEMM phases: per-segment flips deleted, one static s_setprio 1 for waves 4-7 set at each tile-loop header, reset at phase end
# baseline (speedup 1.0000x reference)
; template <class Epi, class Sched, bool ALIGN_EPI = false, bool SP2 = false>
; __device__ __forceinline__ void gemm_phase(PG8_LAS unsigned char* lds, const Gemm g, const Sched& S, const Epi& E) {
;     ...
;     for (;;) {
;         const bool has_next = S.next(ui + 1, nxt);
;         const char* nA = has_next ? (const char*)g.A + (size_t)nxt.pm * tstep : cA; const char* nB = has_next ? (const char*)g.Bt + (size_t)nxt.pn * tstep : cB;
;         for (int t = 0; t < nt; t += 2) {
.LBB0_65:
	v_cmp_lt_u32_e32 vcc, 0xff, v178
	s_cbranch_vccz .Lgprio_skip0
	s_setprio 1

; #define PG8_WAIT_V(n) asm volatile("s_waitcnt vmcnt(" #n ")" ::: "memory")
; #define PG8_BAR __builtin_amdgcn_s_barrier()
; __device__ __forceinline__ unsigned xb_add(unsigned* p, unsigned v) { return __hip_atomic_fetch_add(p, v, __ATOMIC_RELAXED, __HIP_MEMORY_SCOPE_AGENT); }
; template <class Epi, class Sched, bool ALIGN_EPI = false, bool SP2 = false>
; __device__ __forceinline__ void gemm_phase(PG8_LAS unsigned char* lds, const Gemm g, const Sched& S, const Epi& E) {
;     ...
;     PG8_WAIT_V(0);
;     if constexpr (!ALIGN_EPI) { if (wr == 0) PG8_BAR; }
;     PG8_BAR;
; __device__ __forceinline__ void xcd_barrier(const XcdBarrier& b) {
;     asm volatile("s_waitcnt vmcnt(0)" ::: "memory");
;     __syncthreads();
;     if (threadIdx.x == 0) {
;         unsigned* bar = b.bar;
;         __builtin_amdgcn_s_waitcnt(0);
;         unsigned nloc = b.st[0], nx = b.st[1];
;         if (nloc == 0u) { xcd_barrier_complete(bar, b.x, nloc, nx); b.st[0] = nloc; b.st[1] = nx; }
;         const unsigned old = xb_add(&bar[XB_XSUB(b.x)], 1u);
.LBB0_87:
	s_setprio 0
	s_waitcnt vmcnt(0)
	s_waitcnt vmcnt(0)
	s_barrier
	s_mov_b64 s[4:5], exec
	v_readlane_b32 s0, v244, 4
	v_readlane_b32 s1, v244, 5
	s_and_b64 s[0:1], s[4:5], s[0:1]
	s_mov_b64 exec, s[0:1]
	s_cbranch_execz .LBB0_139
	s_add_i32 s0, 0, 0x22400
	v_mov_b32_e32 v0, s0
	s_waitcnt vmcnt(0) expcnt(0) lgkmcnt(0)
	ds_read_b32 v2, v0
	s_add_i32 s0, 0, 0x22404
	v_mov_b32_e32 v0, s0
	ds_read_b32 v0, v0
	s_waitcnt lgkmcnt(1)
	v_cmp_ne_u32_e32 vcc, 0, v2
	s_cbranch_vccnz .LBB0_103
	s_add_u32 s6, s40, 0x1000
	s_addc_u32 s7, s41, 0
	s_add_u32 s8, s40, 0x1100
	s_addc_u32 s9, s41, 0
	s_add_u32 s10, s40, 0x1200
	s_addc_u32 s11, s41, 0
	s_mul_i32 s0, s43, s95
	s_add_u32 s58, s40, 0x1300
	s_mul_i32 s0, s0, s42
	s_addc_u32 s59, s41, 0
	s_mov_b32 s1, 1
	v_mov_b32_e32 v16, 0
	s_branch .LBB0_91

; #define PG8_WAIT_V(n) asm volatile("s_waitcnt vmcnt(" #n ")" ::: "memory")
; #define PG8_BAR __builtin_amdgcn_s_barrier()
; __device__ __forceinline__ unsigned xb_add(unsigned* p, unsigned v) { return __hip_atomic_fetch_add(p, v, __ATOMIC_RELAXED, __HIP_MEMORY_SCOPE_AGENT); }
; template <class Epi, class Sched, bool ALIGN_EPI = false, bool SP2 = false>
; __device__ __forceinline__ void gemm_phase(PG8_LAS unsigned char* lds, const Gemm g, const Sched& S, const Epi& E) {
;     ...
;     PG8_WAIT_V(0);
;     if constexpr (!ALIGN_EPI) { if (wr == 0) PG8_BAR; }
;     PG8_BAR;
; __device__ __forceinline__ void xcd_barrier(const XcdBarrier& b) {
;     asm volatile("s_waitcnt vmcnt(0)" ::: "memory");
;     __syncthreads();
;     if (threadIdx.x == 0) {
;         unsigned* bar = b.bar;
;         __builtin_amdgcn_s_waitcnt(0);
;         unsigned nloc = b.st[0], nx = b.st[1];
;         if (nloc == 0u) { xcd_barrier_complete(bar, b.x, nloc, nx); b.st[0] = nloc; b.st[1] = nx; }
;         const unsigned old = xb_add(&bar[XB_XSUB(b.x)], 1u);
.LBB0_288:
	s_setprio 0
	s_waitcnt vmcnt(0)
	s_waitcnt vmcnt(0)
	s_barrier
	s_mov_b64 s[4:5], exec
	v_readlane_b32 s0, v244, 4
	v_readlane_b32 s1, v244, 5
	s_and_b64 s[0:1], s[4:5], s[0:1]
	s_mov_b64 exec, s[0:1]
	s_cbranch_execz .LBB0_340
	s_add_i32 s0, 0, 0x22400
	v_mov_b32_e32 v0, s0
	s_waitcnt vmcnt(0) expcnt(0) lgkmcnt(0)
	ds_read_b32 v2, v0
	s_add_i32 s0, 0, 0x22404
	v_mov_b32_e32 v0, s0
	ds_read_b32 v0, v0
	s_waitcnt lgkmcnt(1)
	v_cmp_ne_u32_e32 vcc, 0, v2
	s_cbranch_vccnz .LBB0_304
	s_add_u32 s6, s40, 0x1000
	s_addc_u32 s7, s41, 0
	s_add_u32 s8, s40, 0x1100
	s_addc_u32 s9, s41, 0
	s_add_u32 s10, s40, 0x1200
	s_addc_u32 s11, s41, 0
	s_mul_i32 s0, s43, s95
	s_add_u32 s36, s40, 0x1300
	s_mul_i32 s0, s0, s42
	s_addc_u32 s37, s41, 0
	s_mov_b32 s1, 1
	v_mov_b32_e32 v16, 0
	s_branch .LBB0_292

; #define PG8_WAIT_V(n) asm volatile("s_waitcnt vmcnt(" #n ")" ::: "memory")
; #define PG8_BAR __builtin_amdgcn_s_barrier()
; __device__ __forceinline__ unsigned xb_add(unsigned* p, unsigned v) { return __hip_atomic_fetch_add(p, v, __ATOMIC_RELAXED, __HIP_MEMORY_SCOPE_AGENT); }
; template <class Epi, class Sched, bool ALIGN_EPI = false, bool SP2 = false>
; __device__ __forceinline__ void gemm_phase(PG8_LAS unsigned char* lds, const Gemm g, const Sched& S, const Epi& E) {
;     ...
;     PG8_WAIT_V(0);
;     if constexpr (!ALIGN_EPI) { if (wr == 0) PG8_BAR; }
;     PG8_BAR;
; __device__ __forceinline__ void xcd_barrier(const XcdBarrier& b) {
;     asm volatile("s_waitcnt vmcnt(0)" ::: "memory");
;     __syncthreads();
;     if (threadIdx.x == 0) {
;         unsigned* bar = b.bar;
;         __builtin_amdgcn_s_waitcnt(0);
;         unsigned nloc = b.st[0], nx = b.st[1];
;         if (nloc == 0u) { xcd_barrier_complete(bar, b.x, nloc, nx); b.st[0] = nloc; b.st[1] = nx; }
;         const unsigned old = xb_add(&bar[XB_XSUB(b.x)], 1u);
.LBB0_420:
	s_setprio 0
	s_waitcnt vmcnt(0)
	s_barrier
	s_mov_b64 s[4:5], exec
	v_readlane_b32 s0, v244, 4
	v_readlane_b32 s1, v244, 5
	s_and_b64 s[0:1], s[4:5], s[0:1]
	s_mov_b64 exec, s[0:1]
	s_cbranch_execz .LBB0_472
	s_add_i32 s0, 0, 0x22400
	v_mov_b32_e32 v0, s0
	s_waitcnt vmcnt(0) expcnt(0) lgkmcnt(0)
	ds_read_b32 v2, v0
	s_add_i32 s0, 0, 0x22404
	v_mov_b32_e32 v0, s0
	ds_read_b32 v0, v0
	s_waitcnt lgkmcnt(1)
	v_cmp_ne_u32_e32 vcc, 0, v2
	s_cbranch_vccnz .LBB0_436
	s_add_u32 s6, s40, 0x1000
	s_addc_u32 s7, s41, 0
	s_add_u32 s8, s40, 0x1100
	s_addc_u32 s9, s41, 0
	s_add_u32 s10, s40, 0x1200
	s_addc_u32 s11, s41, 0
	s_mul_i32 s0, s43, s95
	s_add_u32 s22, s40, 0x1300
	s_mul_i32 s0, s0, s42
	s_addc_u32 s23, s41, 0
	s_mov_b32 s1, 1
	v_mov_b32_e32 v16, 0
	s_branch .LBB0_424

; #define PG8_WAIT_V(n) asm volatile("s_waitcnt vmcnt(" #n ")" ::: "memory")
; #define PG8_BAR __builtin_amdgcn_s_barrier()
; __device__ __forceinline__ unsigned xb_add(unsigned* p, unsigned v) { return __hip_atomic_fetch_add(p, v, __ATOMIC_RELAXED, __HIP_MEMORY_SCOPE_AGENT); }
; template <class Epi, class Sched, bool ALIGN_EPI = false, bool SP2 = false>
; __device__ __forceinline__ void gemm_phase(PG8_LAS unsigned char* lds, const Gemm g, const Sched& S, const Epi& E) {
;     ...
;     PG8_WAIT_V(0);
;     if constexpr (!ALIGN_EPI) { if (wr == 0) PG8_BAR; }
;     PG8_BAR;
; __device__ __forceinline__ void xcd_barrier(const XcdBarrier& b) {
;     asm volatile("s_waitcnt vmcnt(0)" ::: "memory");
;     __syncthreads();
;     if (threadIdx.x == 0) {
;         unsigned* bar = b.bar;
;         __builtin_amdgcn_s_waitcnt(0);
;         unsigned nloc = b.st[0], nx = b.st[1];
;         if (nloc == 0u) { xcd_barrier_complete(bar, b.x, nloc, nx); b.st[0] = nloc; b.st[1] = nx; }
;         const unsigned old = xb_add(&bar[XB_XSUB(b.x)], 1u);
.LBB0_557:
	s_setprio 0
	s_waitcnt vmcnt(0)
	s_waitcnt vmcnt(0)
	s_barrier
	s_mov_b64 s[2:3], exec
	v_readlane_b32 s0, v244, 4
	v_readlane_b32 s1, v244, 5
	s_and_b64 s[0:1], s[2:3], s[0:1]
	s_mov_b64 exec, s[0:1]
	s_cbranch_execz .LBB0_609
	s_add_i32 s0, 0, 0x22400
	v_mov_b32_e32 v0, s0
	s_waitcnt vmcnt(0) expcnt(0) lgkmcnt(0)
	ds_read_b32 v2, v0
	s_add_i32 s0, 0, 0x22404
	v_mov_b32_e32 v0, s0
	ds_read_b32 v0, v0
	s_waitcnt lgkmcnt(1)
	v_cmp_ne_u32_e32 vcc, 0, v2
	s_cbranch_vccnz .LBB0_573
	s_add_u32 s0, s40, 0x1000
	s_addc_u32 s1, s41, 0
	s_add_u32 s4, s40, 0x1100
	s_addc_u32 s5, s41, 0
	s_add_u32 s6, s40, 0x1200
	s_addc_u32 s7, s41, 0
	s_mul_i32 s16, s43, s95
	s_add_u32 s8, s40, 0x1300
	s_mul_i32 s16, s16, s42
	s_addc_u32 s9, s41, 0
	s_mov_b32 s17, 1
	v_mov_b32_e32 v16, 0
	s_branch .LBB0_561
